# attention: V-frag LDS prefetch under QK MFMAs, SGPR-base addressing for K/V tile loads, drop inline-asm pad nops and redundant lgkmcnt waits
# speedup vs baseline: 1.0183x; 1.0183x over previous
; #define LAS __attribute__((address_space(3)))
; __device__ __forceinline__ int mk_tid(int wid_s) { return wid_s * 64 + lane_id(); }
; template <int MODE>
; __device__ __forceinline__ void attn_phase(const Args& a, bool do_ctx, LAS unsigned char* lds, const int wid_s) {
;     const int tid = mk_tid(wid_s);
;     const int lane = tid & 63, wid = wid_s, ql = lane & 31, hf = lane >> 5, G = gridDim.x;
;     const bf16_t* Q = (const bf16_t*)(a.ws + WS_Q); const bf16_t* KN = (const bf16_t*)(a.ws + WS_KN); const bf16_t* KR = (const bf16_t*)(a.ws + WS_KR);
;     const bf16_t* VT = (const bf16_t*)(a.ws + WS_VT); bf16_t* AC = (bf16_t*)(a.ws + WS_AC);
;     const int nitems = 1024 + (do_ctx ? 32 : 0);
;     LAS unsigned char* const ldsv = lds + 2 * KBUF;
;     for (int it = 0;; ++it) {
;         const long L = (long)it * G + blockIdx.x; if (L >= nitems) break;
;         int b, h, qt, nkt;
;         if (L < 1024) { const int x = (int)(L % 8), q = (int)((L / 8) % 32), bh = (int)(L / 256) * 8 + x; b = bh >> 3; h = bh & 7; qt = q + 1; nkt = RPB / 64; }
;         else { const int bh = (int)(L - 1024); b = bh >> 3; h = bh & 7; qt = 0; nkt = CTXL / 64; }
;         const int rowbase = b * RPB;
;         const int qrow = rowbase + qt * 256 + wid * 32 + ql;
;         bf16x8 qf[6];
; #pragma unroll
;         for (int s = 0; s < 6; ++s) qf[s] = *(const bf16x8*)(Q + (size_t)qrow * 768 + h * 96 + s * 16 + hf * 8);
;         const bf16_t* gkn = KN + ((size_t)(rowbase + (tid >> 3))) * 512 + h * 64 + (tid & 7) * 8;
;         const bf16_t* gkr = KR + ((size_t)(rowbase + ((tid & 255) >> 2))) * 32 + (tid & 3) * 8;
;         const bf16_t* gvt = VT + ((size_t)((b * NH + h) * 64 + (tid >> 3))) * RPB + (tid & 7) * 8;
;         const unsigned skn = (unsigned)((tid >> 3) * KROW + (tid & 7) * 16);
;         const unsigned skr = (unsigned)(((tid & 255) >> 2) * KROW + 128 + (tid & 3) * 16);
;         const unsigned svt = (unsigned)((tid >> 3) * VROW + (tid & 7) * 16);
.LBB0_420:
	s_barrier
	v_mbcnt_lo_u32_b32 v1, -1, 0
	v_mbcnt_hi_u32_b32 v1, -1, v1
	v_readlane_b32 s0, v249, 8
	v_and_b32_e32 v5, 31, v1
	v_readlane_b32 s2, v249, 38
	v_add_u32_e32 v3, s0, v1
	v_and_b32_e32 v4, 63, v1
	v_bfe_u32 v6, v1, 5, 1
	v_or_b32_e32 v158, s2, v5
	v_and_b32_e32 v7, 7, v1
	v_lshlrev_b32_e32 v1, 4, v1
	v_readlane_b32 s2, v249, 50
	v_and_b32_e32 v132, 48, v1
	v_mov_b32_e32 v133, v201
	v_readlane_b32 s3, v249, 51
	v_readlane_b32 s0, v250, 5
	v_lshlrev_b32_e32 v136, 4, v7
	v_lshl_add_u64 v[134:135], s[2:3], 0, v[132:133]
	v_readlane_b32 s2, v249, 58
	v_mov_b32_e32 v137, v201
	v_readlane_b32 s3, v249, 59
	v_readlane_b32 s1, v250, 6
	v_ashrrev_i32_e32 v159, 3, v3
	v_lshl_add_u64 v[138:139], s[2:3], 0, v[136:137]
	s_movk_i32 s3, 0xd0
	s_movk_i32 s2, 0xffb8
	s_and_b64 s[0:1], s[0:1], exec
	v_lshlrev_b32_e32 v0, 3, v6
	v_bfe_u32 v160, v3, 2, 6
	v_mul_lo_u32 v1, v159, s3
	v_mul_lo_u32 v161, v159, s2
	s_movk_i32 s2, 0x100
	v_lshlrev_b32_e32 v4, 2, v4
	s_movk_i32 s0, 0x420
	s_mov_b32 s1, 0
	v_lshlrev_b32_e32 v2, 3, v7
	v_add3_u32 v162, v1, v136, 0
	v_cmp_gt_i32_e64 s[6:7], s2, v3
	v_mad_u32_u24 v1, v160, s3, v132
	v_mad_u32_u24 v3, v5, s3, 0
	v_lshlrev_b32_e32 v7, 4, v6
	v_xor_b32_e32 v163, 0x80, v4
	v_add_u32_e32 v8, 0, v0
	v_mul_u32_u24_e32 v5, 0x88, v5
	v_lshlrev_b32_e32 v4, 2, v6
	s_cselect_b32 s0, s0, 0x400
	v_lshlrev_b32_e32 v200, 1, v0
	v_lshlrev_b32_e32 v140, 1, v2
	v_lshlrev_b32_e32 v142, 1, v4
	v_add_u32_e32 v164, 0, v1
	v_add_u32_e32 v165, v3, v7
	v_add_u32_e32 v166, v8, v5
	v_add_u32_e32 v240, 0x6800, v166
	v_add_u32_e32 v241, 0x7800, v166
	v_add_u32_e32 v242, 0x8800, v166
	v_add_u32_e32 v243, 0x9800, v166
	s_mov_b32 s24, s1
	s_branch .LBB0_423

; #define ATT_LOADK(rk, rr, kt_) do { if (MODE == 3 && (kt_) > 1) break; rk = *(const u32x4*)(gkn + (size_t)(kt_) * 64 * 512); rr = *(const u32x4*)(gkr + (size_t)(kt_) * 64 * 32); } while (0)
; #define ATT_LOADV(rv, kt_) do { if (MODE == 3 && (kt_) > 1) break; rv = *(const u32x4*)(gvt + (size_t)(kt_) * 64); } while (0)
; template <int MODE>
; __device__ __forceinline__ void attn_phase(const Args& a, bool do_ctx, LAS unsigned char* lds, const int wid_s) {
;     ...
;         __syncthreads();
;         f32x16 ot[2], sa[2], sb[2];
; #pragma unroll
;         for (int i = 0; i < 16; ++i) { ot[0][i] = 0.f; ot[1][i] = 0.f; }
;         float mrun = -3.0e38f, lsum = 0.f;
;         attn_qk<MODE>(lds, qf, sa, ql, hf);
;         __syncthreads();
;         for (int t = 0; t < nkt; t += 2) {
;             if (t + 2 < nkt) ATT_LOADK(kK, kR, t + 2);
;             ATT_LOADV(vV, t + 1);
.LBB0_433:
	s_or_b64 exec, exec, s[2:3]
	s_movk_i32 s2, 0x4200
	v_mad_i64_i32 v[84:85], s[2:3], v8, s2, 0
	s_waitcnt lgkmcnt(0)
	s_barrier
	ds_read_b128 v[0:3], v165 offset:6656
	ds_read_b128 v[4:7], v165
	ds_read_b128 v[8:11], v165 offset:32
	ds_read_b128 v[20:23], v165 offset:6688
	ds_read_b128 v[24:27], v165 offset:64
	ds_read_b128 v[28:31], v165 offset:6720
	ds_read_b128 v[64:67], v165 offset:96
	ds_read_b128 v[68:71], v165 offset:6752
	v_ashrrev_i32_e32 v145, 31, v144
	s_waitcnt lgkmcnt(6)
	v_mfma_f32_32x32x16_bf16 v[48:63], v[4:7], v[112:115], 0
	s_mov_b32 s8, s77
	s_mov_b32 s9, s77
	s_mov_b32 s10, s77
	s_mov_b32 s11, s77
	s_mov_b32 s12, s77
	s_mov_b32 s13, s77
	s_mov_b32 s14, s77
	v_mfma_f32_32x32x16_bf16 v[32:47], v[0:3], v[112:115], 0
	s_mov_b32 s15, s77
	s_mov_b32 s16, s77
	s_mov_b32 s17, s77
	s_mov_b32 s18, s77
	s_mov_b32 s19, s77
	s_mov_b32 s20, s77
	s_mov_b32 s21, s77
	s_waitcnt lgkmcnt(5)
	v_mfma_f32_32x32x16_bf16 v[48:63], v[8:11], v[96:99], v[48:63]
	s_mov_b32 s22, s77
	s_mov_b32 s23, s77
	v_mov_b64_e32 v[0:1], s[8:9]
	v_mov_b64_e32 v[2:3], s[10:11]
	v_mov_b64_e32 v[4:5], s[12:13]
	v_mov_b64_e32 v[6:7], s[14:15]
	v_mov_b64_e32 v[8:9], s[16:17]
	s_waitcnt lgkmcnt(4)
	v_mfma_f32_32x32x16_bf16 v[32:47], v[20:23], v[96:99], v[32:47]
	v_mov_b64_e32 v[10:11], s[18:19]
	v_mov_b64_e32 v[12:13], s[20:21]
	v_mov_b64_e32 v[14:15], s[22:23]
	ds_read_b128 v[20:23], v165 offset:128
	ds_read_b128 v[72:75], v165 offset:160
	ds_read_b128 v[76:79], v165 offset:6784
	ds_read_b128 v[80:83], v165 offset:6816
	s_waitcnt lgkmcnt(7)
	v_mfma_f32_32x32x16_bf16 v[48:63], v[24:27], v[100:103], v[48:63]
	v_lshl_add_u64 v[16:17], v[136:137], 0, v[16:17]
	v_lshl_add_u64 v[146:147], v[16:17], 0, s[76:77]
	v_lshl_add_u64 v[148:149], v[132:133], 0, v[18:19]
	v_lshl_add_u64 v[150:151], v[136:137], 0, v[84:85]
	v_mov_b32_e32 v143, 0xff61b1e6
	v_mov_b32_e32 v167, 0
	s_mov_b32 s12, 3
	v_readlane_b32 s18, v247, 57
	v_readlane_b32 s19, v247, 58
	s_nop 3
	s_add_u32 s80, s18, 0x31a07000
	s_addc_u32 s81, s19, 0
	s_add_u32 s82, s18, 0x33ae9000
	s_addc_u32 s83, s19, 0
	s_add_u32 s84, s18, 0x33cf7000
	s_addc_u32 s85, s19, 0
	s_waitcnt lgkmcnt(6)
	v_mfma_f32_32x32x16_bf16 v[32:47], v[28:31], v[100:103], v[32:47]
	s_waitcnt lgkmcnt(0)
	s_barrier
	v_mfma_f32_32x32x16_bf16 v[48:63], v[64:67], v[104:107], v[48:63]
	v_mfma_f32_32x32x16_bf16 v[32:47], v[68:71], v[104:107], v[32:47]
	v_mfma_f32_32x32x16_bf16 v[48:63], v[20:23], v[108:111], v[48:63]
	v_mov_b64_e32 v[30:31], v[14:15]
	v_mov_b64_e32 v[28:29], v[12:13]
	v_mov_b64_e32 v[26:27], v[10:11]
	v_mov_b64_e32 v[24:25], v[8:9]
	v_mov_b64_e32 v[22:23], v[6:7]
	v_mov_b64_e32 v[20:21], v[4:5]
	v_mov_b64_e32 v[18:19], v[2:3]
	v_mfma_f32_32x32x16_bf16 v[32:47], v[76:79], v[108:111], v[32:47]
	v_mov_b64_e32 v[16:17], v[0:1]
	v_mfma_f32_32x32x16_bf16 v[48:63], v[72:75], v[116:119], v[48:63]
	v_mfma_f32_32x32x16_bf16 v[32:47], v[80:83], v[116:119], v[32:47]
	s_branch .LBB0_435
.LBB0_434:
	v_add_f32_e32 v80, 0, v80
	v_add_f32_e32 v80, v81, v80
	v_add_f32_e32 v80, v82, v80
	v_add_f32_e32 v80, v83, v80
	v_add_f32_e32 v80, v84, v80
	v_add_f32_e32 v80, v85, v80
	v_add_f32_e32 v80, v86, v80
	v_add_f32_e32 v80, v87, v80
	v_add_f32_e32 v80, v88, v80
	v_add_f32_e32 v80, v89, v80
	v_add_f32_e32 v80, v90, v80
	v_add_f32_e32 v80, v91, v80
	v_add_f32_e32 v80, v92, v80
	v_add_f32_e32 v80, v93, v80
	v_add_f32_e32 v80, v94, v80
	v_add_f32_e32 v80, v95, v80
	v_add_f32_e32 v64, v64, v80
	v_add_f32_e32 v64, v65, v64
	v_add_f32_e32 v64, v66, v64
	v_add_f32_e32 v64, v67, v64
	v_add_f32_e32 v64, v68, v64
	v_add_f32_e32 v64, v69, v64
	v_add_f32_e32 v64, v70, v64
	v_add_f32_e32 v64, v71, v64
	v_add_f32_e32 v64, v72, v64
	v_add_f32_e32 v64, v73, v64
	v_add_f32_e32 v64, v74, v64
	v_add_f32_e32 v64, v75, v64
	v_add_f32_e32 v64, v76, v64
	v_add_f32_e32 v64, v77, v64
	s_add_u32 s80, s80, 0x20000
	s_addc_u32 s81, s81, 0
	s_add_u32 s82, s82, 0x2000
	s_addc_u32 s83, s83, 0
	s_add_u32 s84, s84, 0x100
	s_addc_u32 s85, s85, 0
	v_add_f32_e32 v64, v78, v64
	v_add_f32_e32 v64, v79, v64
	s_add_i32 s12, s12, 2
	v_add_f32_e32 v167, v167, v64
	s_cmp_ge_u32 s13, s25
	s_waitcnt lgkmcnt(0)
	s_barrier
	s_cbranch_scc1 .LBB0_421
.LBB0_435:
	s_add_i32 s13, s12, -1
	s_cmp_lt_u32 s13, s25
	s_cselect_b64 s[10:11], -1, 0
	s_cmp_ge_u32 s13, s25
	s_cbranch_scc1 .LBB0_437
	global_load_dwordx4 v[120:123], v146, s[80:81]
	global_load_dwordx4 v[124:127], v148, s[82:83]
; #define LAS __attribute__((address_space(3)))
; __device__ __forceinline__ float shx32(float v, int lane) { return __int_as_float(__builtin_amdgcn_ds_bpermute((lane ^ 32) << 2, __float_as_int(v))); }
; template <int MODE>
; __device__ __forceinline__ void attn_qk(const LAS unsigned char* kb_, const bf16x8 (&qf)[6], f32x16 (&st)[2], const int ql, const int hf) {
;     ...
;     bf16x8 ka[4], kc[4], ke[4];
; #pragma unroll
;     for (int s = 0; s < 2; ++s) { ka[2 * s] = ATT_KF(0, s); ka[2 * s + 1] = ATT_KF(1, s); }
; #pragma unroll
;     for (int s = 2; s < 4; ++s) { kc[2 * (s - 2)] = ATT_KF(0, s); kc[2 * (s - 2) + 1] = ATT_KF(1, s); }
;     __builtin_amdgcn_sched_barrier(0);
; #pragma unroll
;     for (int i = 0; i < 16; ++i) { st[0][i] = 0.f; st[1][i] = 0.f; }
; #pragma unroll
;     for (int s = 0; s < 2; ++s) { st[0] = ATT_MMA(ka[2 * s], qf[s], st[0], 0, 0, 0); st[1] = ATT_MMA(ka[2 * s + 1], qf[s], st[1], 0, 0, 0); }
;     __builtin_amdgcn_sched_barrier(0);
; #pragma unroll
;     for (int s = 4; s < 6; ++s) { ke[2 * (s - 4)] = ATT_KF(0, s); ke[2 * (s - 4) + 1] = ATT_KF(1, s); }
;     __builtin_amdgcn_sched_barrier(0);
; #pragma unroll
;     for (int s = 2; s < 4; ++s) { st[0] = ATT_MMA(kc[2 * (s - 2)], qf[s], st[0], 0, 0, 0); st[1] = ATT_MMA(kc[2 * (s - 2) + 1], qf[s], st[1], 0, 0, 0); }
; #pragma unroll
;     for (int s = 4; s < 6; ++s) { st[0] = ATT_MMA(ke[2 * (s - 4)], qf[s], st[0], 0, 0, 0); st[1] = ATT_MMA(ke[2 * (s - 4) + 1], qf[s], st[1], 0, 0, 0); }
;     ...
; }
; template <int MODE>
; __device__ __forceinline__ void attn_pv(const LAS unsigned char* vb_, f32x16 (&st)[2], f32x16 (&ot)[2], float& mrun, float& lsum, const int ql, const int hf, const int lane) {
;     if (MODE != 1) {
;     float mx = max3f(st[0][0], st[1][0], st[0][1]), my = max3f(st[1][1], st[0][2], st[1][2]);
; #pragma unroll
;     for (int i = 3; i < 15; i += 2) { mx = max3f(mx, st[0][i], st[1][i]); my = max3f(my, st[0][i + 1], st[1][i + 1]); }
;     mx = max3f(mx, st[0][15], st[1][15]); mx = max3f(mx, my, my);
;     if (__builtin_amdgcn_ballot_w64(mx > mrun + 8.0f) != 0ull) {
;         mx = fmaxf(mx, shx32(mx, lane));
;         const float mnew = (mx > mrun + 8.0f) ? mx : mrun;
;         const float alpha = fexp2(mrun - mnew);
;         mrun = mnew; lsum *= alpha;
; #pragma unroll
;         for (int i = 0; i < 16; ++i) { ot[0][i] *= alpha; ot[1][i] *= alpha; }
;     }
.LBB0_437:
	global_load_dwordx4 v[128:131], v150, s[84:85] offset:128
	ds_read_b128 v[64:67], v165 offset:13312
	ds_read_b128 v[168:171], v165 offset:13344
	ds_read_b128 v[68:71], v165 offset:19968
	ds_read_b128 v[172:175], v165 offset:20000
	ds_read_b128 v[176:179], v165 offset:13376
	ds_read_b128 v[180:183], v165 offset:13408
	ds_read_b128 v[184:187], v165 offset:20032
	ds_read_b128 v[188:191], v165 offset:20064
	s_waitcnt lgkmcnt(7)
	v_mfma_f32_32x32x16_bf16 v[80:95], v[64:67], v[112:115], 0
	s_waitcnt lgkmcnt(5)
	v_mfma_f32_32x32x16_bf16 v[64:79], v[68:71], v[112:115], 0
	v_mfma_f32_32x32x16_bf16 v[80:95], v[168:171], v[96:99], v[80:95]
	s_waitcnt lgkmcnt(4)
	v_mfma_f32_32x32x16_bf16 v[64:79], v[172:175], v[96:99], v[64:79]
	ds_read_b128 v[168:171], v165 offset:13440
	ds_read_b128 v[172:175], v165 offset:13472
	ds_read_b128 v[192:195], v165 offset:20096
	ds_read_b128 v[196:199], v165 offset:20128
	ds_read2_b64 v[206:209], v241 offset0:32 offset1:34
	ds_read2_b64 v[210:213], v240 offset1:2
	ds_read2_b64 v[214:217], v241 offset0:36 offset1:38
	s_waitcnt lgkmcnt(10)
	v_mfma_f32_32x32x16_bf16 v[80:95], v[176:179], v[100:103], v[80:95]
	s_waitcnt lgkmcnt(8)
	v_mfma_f32_32x32x16_bf16 v[64:79], v[184:187], v[100:103], v[64:79]
	v_mfma_f32_32x32x16_bf16 v[80:95], v[180:183], v[104:107], v[80:95]
	s_waitcnt lgkmcnt(7)
	v_mfma_f32_32x32x16_bf16 v[64:79], v[188:191], v[104:107], v[64:79]
	ds_read2_b64 v[218:221], v240 offset0:4 offset1:6
	ds_read2_b64 v[222:225], v241 offset0:40 offset1:42
	s_waitcnt lgkmcnt(8)
	v_mfma_f32_32x32x16_bf16 v[80:95], v[168:171], v[108:111], v[80:95]
	ds_read2_b64 v[226:229], v240 offset0:8 offset1:10
	ds_read2_b64 v[236:239], v240 offset0:12 offset1:14
	s_waitcnt lgkmcnt(8)
	v_mfma_f32_32x32x16_bf16 v[64:79], v[192:195], v[108:111], v[64:79]
	v_mfma_f32_32x32x16_bf16 v[80:95], v[172:175], v[116:119], v[80:95]
	ds_read2_b64 a[0:3], v241 offset0:44 offset1:46
	s_waitcnt lgkmcnt(8)
	v_mfma_f32_32x32x16_bf16 v[64:79], v[196:199], v[116:119], v[64:79]
	v_max3_f32 v168, v48, v32, v49
	v_max3_f32 v169, v33, v50, v34
	v_max3_f32 v168, v168, v51, v35
	v_max3_f32 v169, v169, v52, v36
	v_max3_f32 v168, v168, v53, v37
	v_max3_f32 v169, v169, v54, v38
	v_max3_f32 v168, v168, v55, v39
	v_max3_f32 v169, v169, v56, v40
	v_max3_f32 v168, v168, v57, v41
	v_max3_f32 v169, v169, v58, v42
	v_max3_f32 v168, v168, v59, v43
	v_max3_f32 v169, v169, v60, v44
	v_max3_f32 v168, v168, v61, v45
	v_max3_f32 v169, v169, v62, v46
	v_max3_f32 v168, v168, v63, v47
	v_max3_f32 v169, v168, v169, v169
	v_add_f32_e32 v168, 0x41000000, v143
	v_cmp_gt_f32_e32 vcc, v169, v168
	s_cbranch_vccz .LBB0_439
	ds_bpermute_b32 v170, v163, v169
	v_max_f32_e32 v169, v169, v169
	s_waitcnt lgkmcnt(0)
	v_max_f32_e32 v170, v170, v170
	v_max_f32_e32 v169, v169, v170
	v_cmp_gt_f32_e32 vcc, v169, v168
	s_nop 1
	v_cndmask_b32_e32 v169, v143, v169, vcc
	v_sub_f32_e32 v143, v143, v169
	v_exp_f32_e32 v168, v143
	v_mov_b32_e32 v143, v169
	v_mul_f32_e32 v167, v167, v168
	v_pk_mul_f32 v[14:15], v[14:15], v[168:169] op_sel_hi:[1,0]
	v_pk_mul_f32 v[12:13], v[12:13], v[168:169] op_sel_hi:[1,0]
	v_pk_mul_f32 v[10:11], v[10:11], v[168:169] op_sel_hi:[1,0]
	v_pk_mul_f32 v[8:9], v[8:9], v[168:169] op_sel_hi:[1,0]
	v_pk_mul_f32 v[6:7], v[6:7], v[168:169] op_sel_hi:[1,0]
	v_pk_mul_f32 v[4:5], v[4:5], v[168:169] op_sel_hi:[1,0]
	v_pk_mul_f32 v[2:3], v[2:3], v[168:169] op_sel_hi:[1,0]
	v_pk_mul_f32 v[0:1], v[0:1], v[168:169] op_sel_hi:[1,0]
	v_pk_mul_f32 v[30:31], v[30:31], v[168:169] op_sel_hi:[1,0]
	v_pk_mul_f32 v[28:29], v[28:29], v[168:169] op_sel_hi:[1,0]
	v_pk_mul_f32 v[26:27], v[26:27], v[168:169] op_sel_hi:[1,0]
	v_pk_mul_f32 v[24:25], v[24:25], v[168:169] op_sel_hi:[1,0]
	v_pk_mul_f32 v[22:23], v[22:23], v[168:169] op_sel_hi:[1,0]
	v_pk_mul_f32 v[20:21], v[20:21], v[168:169] op_sel_hi:[1,0]
	v_pk_mul_f32 v[18:19], v[18:19], v[168:169] op_sel_hi:[1,0]
	v_pk_mul_f32 v[16:17], v[16:17], v[168:169] op_sel_hi:[1,0]
; #define LAS __attribute__((address_space(3)))
; __device__ __forceinline__ unsigned pk_bf16(float lo, float hi) { unsigned r; asm("v_cvt_pk_bf16_f32 %0, %1, %2" : "=v"(r) : "v"(lo), "v"(hi)); return r; }
; __device__ __forceinline__ float fexp2(float x) { return __builtin_amdgcn_exp2f(x); }
; template <int MODE>
; __device__ __forceinline__ void attn_pv(const LAS unsigned char* vb_, f32x16 (&st)[2], f32x16 (&ot)[2], float& mrun, float& lsum, const int ql, const int hf, const int lane) {
;     ...
;     float ps = 0.f;
; #pragma unroll
;     for (int kb = 0; kb < 2; ++kb)
; #pragma unroll
;         for (int i = 0; i < 16; ++i) { const float p = fexp2(st[kb][i] - mrun); st[kb][i] = p; ps += p; }
;     lsum += ps;
;     } else lsum += st[0][0];
; #pragma unroll
;     for (int kb = 0; kb < 2; ++kb)
; #pragma unroll
;         for (int sI = 0; sI < 2; ++sI) {
;             u32x4 pw = {pk_bf16(st[kb][8 * sI + 0], st[kb][8 * sI + 1]), pk_bf16(st[kb][8 * sI + 2], st[kb][8 * sI + 3]),
;                         pk_bf16(st[kb][8 * sI + 4], st[kb][8 * sI + 5]), pk_bf16(st[kb][8 * sI + 6], st[kb][8 * sI + 7])};
;             const bf16x8 pf = __builtin_bit_cast(bf16x8, pw);
; #pragma unroll
;             for (int db = 0; db < 2; ++db) {
;                 const LAS unsigned char* vp = vb_ + (db * 32 + ql) * VROW + (kb * 32 + 16 * sI + 4 * hf) * 2;
;                 const u32x2 v0 = *(const LAS u32x2*)vp, v1 = *(const LAS u32x2*)(vp + 16);
;                 u32x4 vw = {v0[0], v0[1], v1[0], v1[1]};
;                 ot[db] = att_mma<MODE>(__builtin_bit_cast(bf16x8, vw), pf, ot[db]);
;             }
;         }
; }
.LBB0_439:
	v_sub_f32_e32 v48, v48, v143
	v_exp_f32_e32 v168, v48
	v_sub_f32_e32 v48, v49, v143
	v_exp_f32_e32 v169, v48
	v_sub_f32_e32 v48, v50, v143
	v_exp_f32_e32 v170, v48
	v_sub_f32_e32 v48, v51, v143
	v_exp_f32_e32 v171, v48
	v_sub_f32_e32 v48, v52, v143
	v_exp_f32_e32 v172, v48
	v_sub_f32_e32 v48, v53, v143
	v_exp_f32_e32 v173, v48
	v_sub_f32_e32 v48, v54, v143
	v_exp_f32_e32 v174, v48
	v_sub_f32_e32 v48, v55, v143
	v_exp_f32_e32 v175, v48
	v_sub_f32_e32 v48, v56, v143
	v_exp_f32_e32 v176, v48
	v_sub_f32_e32 v48, v57, v143
	v_exp_f32_e32 v177, v48
	v_sub_f32_e32 v48, v58, v143
	v_exp_f32_e32 v178, v48
	v_sub_f32_e32 v48, v59, v143
	v_exp_f32_e32 v179, v48
	v_sub_f32_e32 v48, v60, v143
	v_exp_f32_e32 v180, v48
	v_sub_f32_e32 v48, v61, v143
	v_exp_f32_e32 v181, v48
	v_sub_f32_e32 v48, v62, v143
	v_exp_f32_e32 v182, v48
	v_sub_f32_e32 v48, v63, v143
	v_exp_f32_e32 v183, v48
	v_sub_f32_e32 v32, v32, v143
	v_sub_f32_e32 v36, v36, v143
	v_exp_f32_e32 v184, v32
	v_sub_f32_e32 v32, v33, v143
	v_exp_f32_e32 v188, v36
	v_sub_f32_e32 v36, v37, v143
	v_exp_f32_e32 v185, v32
	v_sub_f32_e32 v32, v34, v143
	v_exp_f32_e32 v189, v36
	v_sub_f32_e32 v36, v38, v143
	v_exp_f32_e32 v186, v32
	v_sub_f32_e32 v57, v35, v143
	v_cvt_pk_bf16_f32 v32, v168, v169
	v_cvt_pk_bf16_f32 v33, v170, v171
	v_cvt_pk_bf16_f32 v34, v172, v173
	v_cvt_pk_bf16_f32 v35, v174, v175
	v_exp_f32_e32 v190, v36
	s_waitcnt lgkmcnt(0)
	v_mfma_f32_32x32x16_bf16 v[16:31], v[206:209], v[32:35], v[16:31]
	v_sub_f32_e32 v52, v39, v143
	v_sub_f32_e32 v40, v40, v143
	v_exp_f32_e32 v192, v40
	v_sub_f32_e32 v40, v41, v143
	v_exp_f32_e32 v193, v40
	v_sub_f32_e32 v40, v42, v143
	v_mfma_f32_32x32x16_bf16 v[0:15], v[210:213], v[32:35], v[0:15]
	v_cvt_pk_bf16_f32 v32, v176, v177
	v_cvt_pk_bf16_f32 v33, v178, v179
	v_cvt_pk_bf16_f32 v34, v180, v181
	v_cvt_pk_bf16_f32 v35, v182, v183
	v_exp_f32_e32 v194, v40
	v_sub_f32_e32 v40, v43, v143
	v_mfma_f32_32x32x16_bf16 v[16:31], v[214:217], v[32:35], v[16:31]
	v_exp_f32_e32 v195, v40
	v_sub_f32_e32 v40, v44, v143
	v_exp_f32_e32 v196, v40
	v_sub_f32_e32 v40, v45, v143
	v_exp_f32_e32 v187, v57
	v_exp_f32_e32 v191, v52
	v_mfma_f32_32x32x16_bf16 v[0:15], v[218:221], v[32:35], v[0:15]
	v_cvt_pk_bf16_f32 v32, v184, v185
	v_cvt_pk_bf16_f32 v33, v186, v187
	v_cvt_pk_bf16_f32 v34, v188, v189
	v_cvt_pk_bf16_f32 v35, v190, v191
	v_exp_f32_e32 v197, v40
	s_waitcnt lgkmcnt(0)
	v_mfma_f32_32x32x16_bf16 v[16:31], v[222:225], v[32:35], v[16:31]
	v_sub_f32_e32 v44, v46, v143
	v_exp_f32_e32 v198, v44
	s_andn2_b64 vcc, exec, s[10:11]
	v_mfma_f32_32x32x16_bf16 v[0:15], v[226:229], v[32:35], v[0:15]
	v_sub_f32_e32 v32, v47, v143
	v_exp_f32_e32 v199, v32
	v_cvt_pk_bf16_f32 v32, v192, v193
	v_cvt_pk_bf16_f32 v33, v194, v195
	v_cvt_pk_bf16_f32 v34, v196, v197
	v_cvt_pk_bf16_f32 v35, v198, v199
	s_nop 1
	v_mfma_f32_32x32x16_bf16 v[0:15], v[236:239], v[32:35], v[0:15]
	s_not_b64 s[8:9], s[10:11]
	v_mfma_f32_32x32x16_bf16 v[16:31], a[0:3], v[32:35], v[16:31]
	s_cbranch_vccnz .LBB0_443
	s_waitcnt vmcnt(2)
	ds_write_b128 v162, v[120:123]
	s_and_saveexec_b64 s[2:3], s[6:7]
	s_cbranch_execz .LBB0_442
	s_waitcnt vmcnt(1)
	ds_write_b128 v164, v[124:127] offset:128

; __device__ __forceinline__ float fexp2(float x) { return __builtin_amdgcn_exp2f(x); }
; #define ATT_LOADK(rk, rr, kt_) do { if (MODE == 3 && (kt_) > 1) break; rk = *(const u32x4*)(gkn + (size_t)(kt_) * 64 * 512); rr = *(const u32x4*)(gkr + (size_t)(kt_) * 64 * 32); } while (0)
; #define ATT_LOADV(rv, kt_) do { if (MODE == 3 && (kt_) > 1) break; rv = *(const u32x4*)(gvt + (size_t)(kt_) * 64); } while (0)
; #define ATT_WRITEK(rk, rr, buf) do { LAS unsigned char* nb_ = lds + (buf) * KBUF; *(LAS u32x4*)(nb_ + skn) = rk; if (tid < 256) *(LAS u32x4*)(nb_ + skr) = rr; } while (0)
; #define ATT_WRITEV(rv, buf) do { LAS u32x2* p_ = (LAS u32x2*)(ldsv + (buf) * VBUF + svt); u32x2 lo_ = {rv[0], rv[1]}, hi_ = {rv[2], rv[3]}; p_[0] = lo_; p_[1] = hi_; } while (0)
; template <int MODE>
; __device__ __forceinline__ void attn_pv(const LAS unsigned char* vb_, f32x16 (&st)[2], f32x16 (&ot)[2], float& mrun, float& lsum, const int ql, const int hf, const int lane) {
;     ...
;     float ps = 0.f;
; #pragma unroll
;     for (int kb = 0; kb < 2; ++kb)
; #pragma unroll
;         for (int i = 0; i < 16; ++i) { const float p = fexp2(st[kb][i] - mrun); st[kb][i] = p; ps += p; }
;     lsum += ps;
; template <int MODE>
; __device__ __forceinline__ void attn_phase(const Args& a, bool do_ctx, LAS unsigned char* lds, const int wid_s) {
;     ...
;             if (t + 2 < nkt) ATT_WRITEK(kK, kR, 0);
;             ATT_WRITEV(vV, 1);
;             __syncthreads();
;             if (t + 3 < nkt) ATT_LOADK(kK, kR, t + 3);
;             if (t + 2 < nkt) ATT_LOADV(vV, t + 2);
.LBB0_443:
	s_mov_b32 s2, 0x8a00
	s_cmp_lt_u32 s12, s25
	v_add3_u32 v32, v162, v161, s2
	s_cselect_b64 s[10:11], -1, 0
	s_cmp_ge_u32 s12, s25
	s_waitcnt vmcnt(0)
	ds_write2_b64 v32, v[128:129], v[130:131] offset1:1
	v_add_f32_e32 v230, 0, v168
	v_add_f32_e32 v230, v169, v230
	v_add_f32_e32 v230, v170, v230
	v_add_f32_e32 v230, v171, v230
	v_add_f32_e32 v230, v172, v230
	v_add_f32_e32 v230, v173, v230
	v_add_f32_e32 v230, v174, v230
	v_add_f32_e32 v230, v175, v230
	v_add_f32_e32 v230, v176, v230
	v_add_f32_e32 v230, v177, v230
	v_add_f32_e32 v230, v178, v230
	v_add_f32_e32 v230, v179, v230
	v_add_f32_e32 v230, v180, v230
	v_add_f32_e32 v230, v181, v230
	v_add_f32_e32 v230, v182, v230
	v_add_f32_e32 v230, v183, v230
	v_add_f32_e32 v230, v184, v230
	v_add_f32_e32 v230, v185, v230
	v_add_f32_e32 v230, v186, v230
	v_add_f32_e32 v230, v187, v230
	v_add_f32_e32 v230, v188, v230
	v_add_f32_e32 v230, v189, v230
	v_add_f32_e32 v230, v190, v230
	v_add_f32_e32 v230, v191, v230
	v_add_f32_e32 v230, v192, v230
	v_add_f32_e32 v230, v193, v230
	v_add_f32_e32 v230, v194, v230
	v_add_f32_e32 v230, v195, v230
	v_add_f32_e32 v230, v196, v230
	v_add_f32_e32 v230, v197, v230
	v_add_f32_e32 v230, v198, v230
	v_add_f32_e32 v230, v199, v230
	v_add_f32_e32 v167, v167, v230
	s_waitcnt lgkmcnt(0)
	s_barrier
	s_cbranch_scc1 .LBB0_447
	s_add_u32 s86, s80, 0x10000
	s_addc_u32 s87, s81, 0
	s_add_u32 s88, s82, 0x1000
	s_addc_u32 s89, s83, 0
	global_load_dwordx4 v[120:123], v146, s[86:87]
	global_load_dwordx4 v[124:127], v148, s[88:89]
	s_and_b64 vcc, exec, s[8:9]
	s_cbranch_vccz .LBB0_448

; #define LAS __attribute__((address_space(3)))
; #define ATT_MMA(a_, b_, c_, x_, y_, z_) att_mma<MODE>(a_, b_, c_)
; template <int MODE>
; __device__ __forceinline__ void attn_qk(const LAS unsigned char* kb_, const bf16x8 (&qf)[6], f32x16 (&st)[2], const int ql, const int hf) {
;     ...
;     bf16x8 ka[4], kc[4], ke[4];
; #pragma unroll
;     for (int s = 0; s < 2; ++s) { ka[2 * s] = ATT_KF(0, s); ka[2 * s + 1] = ATT_KF(1, s); }
; #pragma unroll
;     for (int s = 2; s < 4; ++s) { kc[2 * (s - 2)] = ATT_KF(0, s); kc[2 * (s - 2) + 1] = ATT_KF(1, s); }
;     __builtin_amdgcn_sched_barrier(0);
; #pragma unroll
;     for (int i = 0; i < 16; ++i) { st[0][i] = 0.f; st[1][i] = 0.f; }
; #pragma unroll
;     for (int s = 0; s < 2; ++s) { st[0] = ATT_MMA(ka[2 * s], qf[s], st[0], 0, 0, 0); st[1] = ATT_MMA(ka[2 * s + 1], qf[s], st[1], 0, 0, 0); }
;     __builtin_amdgcn_sched_barrier(0);
; #pragma unroll
;     for (int s = 4; s < 6; ++s) { ke[2 * (s - 4)] = ATT_KF(0, s); ke[2 * (s - 4) + 1] = ATT_KF(1, s); }
;     __builtin_amdgcn_sched_barrier(0);
; #pragma unroll
;     for (int s = 2; s < 4; ++s) { st[0] = ATT_MMA(kc[2 * (s - 2)], qf[s], st[0], 0, 0, 0); st[1] = ATT_MMA(kc[2 * (s - 2) + 1], qf[s], st[1], 0, 0, 0); }
; #pragma unroll
;     for (int s = 4; s < 6; ++s) { st[0] = ATT_MMA(ke[2 * (s - 4)], qf[s], st[0], 0, 0, 0); st[1] = ATT_MMA(ke[2 * (s - 4) + 1], qf[s], st[1], 0, 0, 0); }
;     ...
; }
.LBB0_446:
	ds_read_b128 v[32:35], v165
	ds_read_b128 v[152:155], v165 offset:32
	ds_read_b128 v[36:39], v165 offset:6656
	ds_read_b128 v[206:209], v165 offset:6688
	ds_read_b128 v[210:213], v165 offset:64
	ds_read_b128 v[214:217], v165 offset:96
	ds_read_b128 v[218:221], v165 offset:6720
	ds_read_b128 v[222:225], v165 offset:6752
	s_waitcnt lgkmcnt(7)
	v_mfma_f32_32x32x16_bf16 v[48:63], v[32:35], v[112:115], 0
	s_waitcnt lgkmcnt(5)
	v_mfma_f32_32x32x16_bf16 v[32:47], v[36:39], v[112:115], 0
	v_mfma_f32_32x32x16_bf16 v[48:63], v[152:155], v[96:99], v[48:63]
	s_waitcnt lgkmcnt(4)
	v_mfma_f32_32x32x16_bf16 v[32:47], v[206:209], v[96:99], v[32:47]
	ds_read_b128 v[152:155], v165 offset:128
	ds_read_b128 v[206:209], v165 offset:160
	ds_read_b128 v[226:229], v165 offset:6784
	ds_read_b128 v[236:239], v165 offset:6816
	ds_read2_b64 v[176:179], v242 offset0:64 offset1:66
	ds_read2_b64 v[180:183], v243 offset0:96 offset1:98
	ds_read2_b64 v[184:187], v242 offset0:68 offset1:70
	s_waitcnt lgkmcnt(10)
	v_mfma_f32_32x32x16_bf16 v[48:63], v[210:213], v[100:103], v[48:63]
	s_waitcnt lgkmcnt(8)
	v_mfma_f32_32x32x16_bf16 v[32:47], v[218:221], v[100:103], v[32:47]
	v_mfma_f32_32x32x16_bf16 v[48:63], v[214:217], v[104:107], v[48:63]
	s_waitcnt lgkmcnt(7)
	v_mfma_f32_32x32x16_bf16 v[32:47], v[222:225], v[104:107], v[32:47]
	ds_read2_b64 v[188:191], v243 offset0:100 offset1:102
	ds_read2_b64 v[192:195], v242 offset0:72 offset1:74
	s_waitcnt lgkmcnt(8)
	v_mfma_f32_32x32x16_bf16 v[48:63], v[152:155], v[108:111], v[48:63]
	ds_read2_b64 v[196:199], v243 offset0:104 offset1:106
	ds_read2_b64 v[172:175], v242 offset0:76 offset1:78
	s_waitcnt lgkmcnt(8)
	v_mfma_f32_32x32x16_bf16 v[32:47], v[226:229], v[108:111], v[32:47]
	v_mfma_f32_32x32x16_bf16 v[48:63], v[206:209], v[116:119], v[48:63]
	ds_read2_b64 a[0:3], v243 offset0:108 offset1:110
	s_waitcnt lgkmcnt(8)
	v_mfma_f32_32x32x16_bf16 v[32:47], v[236:239], v[116:119], v[32:47]
	s_branch .LBB0_450

; #define LAS __attribute__((address_space(3)))
; __device__ __forceinline__ float shx32(float v, int lane) { return __int_as_float(__builtin_amdgcn_ds_bpermute((lane ^ 32) << 2, __float_as_int(v))); }
; __device__ __forceinline__ unsigned pk_bf16(float lo, float hi) { unsigned r; asm("v_cvt_pk_bf16_f32 %0, %1, %2" : "=v"(r) : "v"(lo), "v"(hi)); return r; }
; template <int MODE>
; __device__ __forceinline__ void attn_pv(const LAS unsigned char* vb_, f32x16 (&st)[2], f32x16 (&ot)[2], float& mrun, float& lsum, const int ql, const int hf, const int lane) {
;     if (MODE != 1) {
;     float mx = max3f(st[0][0], st[1][0], st[0][1]), my = max3f(st[1][1], st[0][2], st[1][2]);
; #pragma unroll
;     for (int i = 3; i < 15; i += 2) { mx = max3f(mx, st[0][i], st[1][i]); my = max3f(my, st[0][i + 1], st[1][i + 1]); }
;     mx = max3f(mx, st[0][15], st[1][15]); mx = max3f(mx, my, my);
;     if (__builtin_amdgcn_ballot_w64(mx > mrun + 8.0f) != 0ull) {
;         mx = fmaxf(mx, shx32(mx, lane));
;         const float mnew = (mx > mrun + 8.0f) ? mx : mrun;
;         const float alpha = fexp2(mrun - mnew);
;         mrun = mnew; lsum *= alpha;
; #pragma unroll
;         for (int i = 0; i < 16; ++i) { ot[0][i] *= alpha; ot[1][i] *= alpha; }
;     }
;     float ps = 0.f;
; #pragma unroll
;     for (int kb = 0; kb < 2; ++kb)
; #pragma unroll
;         for (int i = 0; i < 16; ++i) { const float p = fexp2(st[kb][i] - mrun); st[kb][i] = p; ps += p; }
;     lsum += ps;
;     } else lsum += st[0][0];
; #pragma unroll
;     for (int kb = 0; kb < 2; ++kb)
; #pragma unroll
;         for (int sI = 0; sI < 2; ++sI) {
;             u32x4 pw = {pk_bf16(st[kb][8 * sI + 0], st[kb][8 * sI + 1]), pk_bf16(st[kb][8 * sI + 2], st[kb][8 * sI + 3]),
;                         pk_bf16(st[kb][8 * sI + 4], st[kb][8 * sI + 5]), pk_bf16(st[kb][8 * sI + 6], st[kb][8 * sI + 7])};
;             const bf16x8 pf = __builtin_bit_cast(bf16x8, pw);
; #pragma unroll
;             for (int db = 0; db < 2; ++db) {
;                 const LAS unsigned char* vp = vb_ + (db * 32 + ql) * VROW + (kb * 32 + 16 * sI + 4 * hf) * 2;
;                 const u32x2 v0 = *(const LAS u32x2*)vp, v1 = *(const LAS u32x2*)(vp + 16);
;                 u32x4 vw = {v0[0], v0[1], v1[0], v1[1]};
;                 ot[db] = att_mma<MODE>(__builtin_bit_cast(bf16x8, vw), pf, ot[db]);
;             }
;         }
; }
.LBB0_448:
	global_load_dwordx4 v[128:131], v150, s[84:85] offset:256
	s_and_b64 vcc, exec, s[8:9]
	s_cbranch_vccz .LBB0_446
.LBB0_449:
	ds_read2_b64 v[176:179], v242 offset0:64 offset1:66
	ds_read2_b64 v[180:183], v243 offset0:96 offset1:98
	ds_read2_b64 v[184:187], v242 offset0:68 offset1:70
	ds_read2_b64 v[188:191], v243 offset0:100 offset1:102
	ds_read2_b64 v[192:195], v242 offset0:72 offset1:74
	ds_read2_b64 v[196:199], v243 offset0:104 offset1:106
	ds_read2_b64 v[172:175], v242 offset0:76 offset1:78
	ds_read2_b64 a[0:3], v243 offset0:108 offset1:110
.LBB0_450:
	v_max3_f32 v153, v80, v64, v81
	v_max3_f32 v154, v65, v82, v66
	v_max3_f32 v153, v153, v83, v67
	v_max3_f32 v154, v154, v84, v68
	v_max3_f32 v153, v153, v85, v69
	v_max3_f32 v154, v154, v86, v70
	v_max3_f32 v153, v153, v87, v71
	v_max3_f32 v154, v154, v88, v72
	v_max3_f32 v153, v153, v89, v73
	v_max3_f32 v154, v154, v90, v74
	v_max3_f32 v153, v153, v91, v75
	v_max3_f32 v154, v154, v92, v76
	v_max3_f32 v153, v153, v93, v77
	v_max3_f32 v154, v154, v94, v78
	v_max3_f32 v153, v153, v95, v79
	v_max3_f32 v154, v153, v154, v154
	v_add_f32_e32 v153, 0x41000000, v143
	v_cmp_gt_f32_e32 vcc, v154, v153
	s_cbranch_vccz .LBB0_452
	ds_bpermute_b32 v155, v163, v154
	v_max_f32_e32 v154, v154, v154
	s_waitcnt lgkmcnt(0)
	v_max_f32_e32 v155, v155, v155
	v_max_f32_e32 v154, v154, v155
	v_cmp_gt_f32_e32 vcc, v154, v153
	s_nop 1
	v_cndmask_b32_e32 v153, v143, v154, vcc
	v_sub_f32_e32 v143, v143, v153
	v_exp_f32_e32 v154, v143
	v_mov_b32_e32 v143, v153
	v_mul_f32_e32 v167, v167, v154
	v_pk_mul_f32 v[14:15], v[14:15], v[154:155] op_sel_hi:[1,0]
	v_pk_mul_f32 v[12:13], v[12:13], v[154:155] op_sel_hi:[1,0]
	v_pk_mul_f32 v[10:11], v[10:11], v[154:155] op_sel_hi:[1,0]
	v_pk_mul_f32 v[8:9], v[8:9], v[154:155] op_sel_hi:[1,0]
	v_pk_mul_f32 v[6:7], v[6:7], v[154:155] op_sel_hi:[1,0]
	v_pk_mul_f32 v[4:5], v[4:5], v[154:155] op_sel_hi:[1,0]
	v_pk_mul_f32 v[2:3], v[2:3], v[154:155] op_sel_hi:[1,0]
	v_pk_mul_f32 v[0:1], v[0:1], v[154:155] op_sel_hi:[1,0]
	v_pk_mul_f32 v[30:31], v[30:31], v[154:155] op_sel_hi:[1,0]
	v_pk_mul_f32 v[28:29], v[28:29], v[154:155] op_sel_hi:[1,0]
	v_pk_mul_f32 v[26:27], v[26:27], v[154:155] op_sel_hi:[1,0]
	v_pk_mul_f32 v[24:25], v[24:25], v[154:155] op_sel_hi:[1,0]
	v_pk_mul_f32 v[22:23], v[22:23], v[154:155] op_sel_hi:[1,0]
	v_pk_mul_f32 v[20:21], v[20:21], v[154:155] op_sel_hi:[1,0]
	v_pk_mul_f32 v[18:19], v[18:19], v[154:155] op_sel_hi:[1,0]
	v_pk_mul_f32 v[16:17], v[16:17], v[154:155] op_sel_hi:[1,0]
.LBB0_452:
	v_sub_f32_e32 v80, v80, v143
	v_sub_f32_e32 v81, v81, v143
	v_sub_f32_e32 v82, v82, v143
	v_sub_f32_e32 v83, v83, v143
	v_sub_f32_e32 v84, v84, v143
	v_sub_f32_e32 v85, v85, v143
	v_sub_f32_e32 v86, v86, v143
	v_sub_f32_e32 v87, v87, v143
	v_exp_f32_e32 v80, v80
	v_exp_f32_e32 v81, v81
	v_exp_f32_e32 v82, v82
	v_exp_f32_e32 v83, v83
	v_exp_f32_e32 v84, v84
	v_exp_f32_e32 v85, v85
	v_exp_f32_e32 v86, v86
	v_exp_f32_e32 v87, v87
	v_cvt_pk_bf16_f32 v168, v80, v81
	v_cvt_pk_bf16_f32 v169, v82, v83
	v_cvt_pk_bf16_f32 v170, v84, v85
	v_cvt_pk_bf16_f32 v171, v86, v87
	s_nop 0
	s_waitcnt lgkmcnt(0)
	v_mfma_f32_32x32x16_bf16 v[0:15], v[176:179], v[168:171], v[0:15]
	v_sub_f32_e32 v88, v88, v143
	v_sub_f32_e32 v89, v89, v143
	v_sub_f32_e32 v90, v90, v143
	v_sub_f32_e32 v91, v91, v143
	v_sub_f32_e32 v92, v92, v143
	v_sub_f32_e32 v93, v93, v143
	v_sub_f32_e32 v94, v94, v143
	v_sub_f32_e32 v95, v95, v143
	v_exp_f32_e32 v88, v88
	v_exp_f32_e32 v89, v89
	v_exp_f32_e32 v90, v90
	v_exp_f32_e32 v91, v91
	v_exp_f32_e32 v92, v92
	v_exp_f32_e32 v93, v93
	v_exp_f32_e32 v94, v94
	v_exp_f32_e32 v95, v95
	v_mfma_f32_32x32x16_bf16 v[16:31], v[180:183], v[168:171], v[16:31]
	v_cvt_pk_bf16_f32 v168, v88, v89
	v_cvt_pk_bf16_f32 v169, v90, v91
	v_cvt_pk_bf16_f32 v170, v92, v93
	v_cvt_pk_bf16_f32 v171, v94, v95
	v_sub_f32_e32 v64, v64, v143
	v_sub_f32_e32 v65, v65, v143
	v_mfma_f32_32x32x16_bf16 v[0:15], v[184:187], v[168:171], v[0:15]
	v_sub_f32_e32 v66, v66, v143
	v_sub_f32_e32 v67, v67, v143
	v_sub_f32_e32 v68, v68, v143
	v_sub_f32_e32 v69, v69, v143
	v_sub_f32_e32 v70, v70, v143
	v_sub_f32_e32 v71, v71, v143
	v_exp_f32_e32 v64, v64
	v_exp_f32_e32 v65, v65
	v_exp_f32_e32 v66, v66
	v_exp_f32_e32 v67, v67
	v_exp_f32_e32 v68, v68
	v_exp_f32_e32 v69, v69
	v_exp_f32_e32 v70, v70
	v_exp_f32_e32 v71, v71
	v_mfma_f32_32x32x16_bf16 v[16:31], v[188:191], v[168:171], v[16:31]
	v_cvt_pk_bf16_f32 v168, v64, v65
	v_cvt_pk_bf16_f32 v169, v66, v67
	v_cvt_pk_bf16_f32 v170, v68, v69
	v_cvt_pk_bf16_f32 v171, v70, v71
	v_sub_f32_e32 v72, v72, v143
	v_sub_f32_e32 v73, v73, v143
	v_mfma_f32_32x32x16_bf16 v[0:15], v[192:195], v[168:171], v[0:15]
	v_sub_f32_e32 v74, v74, v143
	v_sub_f32_e32 v75, v75, v143
	v_sub_f32_e32 v76, v76, v143
	v_sub_f32_e32 v77, v77, v143
	v_sub_f32_e32 v78, v78, v143
	v_sub_f32_e32 v79, v79, v143
	v_exp_f32_e32 v72, v72
	v_exp_f32_e32 v73, v73
	v_exp_f32_e32 v74, v74
	v_exp_f32_e32 v75, v75
	v_exp_f32_e32 v76, v76
	v_exp_f32_e32 v77, v77
	v_mfma_f32_32x32x16_bf16 v[16:31], v[196:199], v[168:171], v[16:31]
	v_exp_f32_e32 v78, v78
	v_exp_f32_e32 v79, v79
	v_cvt_pk_bf16_f32 v168, v72, v73
	v_cvt_pk_bf16_f32 v169, v74, v75
	v_cvt_pk_bf16_f32 v170, v76, v77
	v_cvt_pk_bf16_f32 v171, v78, v79
	s_andn2_b64 vcc, exec, s[10:11]
	s_waitcnt lgkmcnt(0)
	v_mfma_f32_32x32x16_bf16 v[0:15], v[172:175], v[168:171], v[0:15]
	v_mfma_f32_32x32x16_bf16 v[16:31], a[0:3], v[168:171], v[16:31]
	s_cbranch_vccnz .LBB0_456
	s_waitcnt vmcnt(1)
	ds_write_b128 v162, v[120:123] offset:13312
	s_and_saveexec_b64 s[2:3], s[6:7]
	s_cbranch_execz .LBB0_455
	s_waitcnt vmcnt(0)
	ds_write_b128 v164, v[124:127] offset:13440

; #define LAS __attribute__((address_space(3)))
; __global__ void __launch_bounds__(NTHREADS, 2) mk_fwd(Args a) {
;     extern __shared__ __attribute__((aligned(16))) unsigned char lds[];
;     cg::grid_group grid = cg::this_grid();
;     LAS unsigned char* ldsl = (LAS unsigned char*)lds;
;     const int G = gridDim.x, bid = blockIdx.x;
;     const int wid_s = __builtin_amdgcn_readfirstlane((int)(threadIdx.x >> 6));
	.amdhsa_kernel _Z6mk_fwd4Args
		.amdhsa_group_segment_fixed_size 0
		.amdhsa_private_segment_fixed_size 0
		.amdhsa_kernarg_size 496
		.amdhsa_user_sgpr_count 2
		.amdhsa_user_sgpr_dispatch_ptr 0
		.amdhsa_user_sgpr_queue_ptr 0
		.amdhsa_user_sgpr_kernarg_segment_ptr 1
		.amdhsa_user_sgpr_dispatch_id 0
		.amdhsa_user_sgpr_kernarg_preload_length 0
		.amdhsa_user_sgpr_kernarg_preload_offset 0
		.amdhsa_user_sgpr_private_segment_size 0
		.amdhsa_uses_dynamic_stack 0
		.amdhsa_enable_private_segment 0
		.amdhsa_system_sgpr_workgroup_id_x 1
		.amdhsa_system_sgpr_workgroup_id_y 0
		.amdhsa_system_sgpr_workgroup_id_z 0
		.amdhsa_system_sgpr_workgroup_info 0
		.amdhsa_system_vgpr_workitem_id 2
		.amdhsa_next_free_vgpr 256
		.amdhsa_next_free_sgpr 100
		.amdhsa_accum_offset 252
		.amdhsa_reserve_vcc 1
		.amdhsa_float_round_mode_32 0
		.amdhsa_float_round_mode_16_64 0
		.amdhsa_float_denorm_mode_32 3
		.amdhsa_float_denorm_mode_16_64 3
		.amdhsa_dx10_clamp 1
		.amdhsa_ieee_mode 1
		.amdhsa_fp16_overflow 0
		.amdhsa_tg_split 0
		.amdhsa_exception_fp_ieee_invalid_op 0
		.amdhsa_exception_fp_denorm_src 0
		.amdhsa_exception_fp_ieee_div_zero 0
		.amdhsa_exception_fp_ieee_overflow 0
		.amdhsa_exception_fp_ieee_underflow 0
		.amdhsa_exception_fp_ieee_inexact 0
		.amdhsa_exception_int_div_zero 0
	.end_amdhsa_kernel

; __global__ void __launch_bounds__(NTHREADS, 2) mk_fwd(Args a) {
;     extern __shared__ __attribute__((aligned(16))) unsigned char lds[];
amdhsa.kernels:
  - .agpr_count:     4
    .args:
      - .offset:         0
        .size:           240
        .value_kind:     by_value
      - .offset:         240
        .size:           4
        .value_kind:     hidden_block_count_x
      - .offset:         244
        .size:           4
        .value_kind:     hidden_block_count_y
      - .offset:         248
        .size:           4
        .value_kind:     hidden_block_count_z
      - .offset:         252
        .size:           2
        .value_kind:     hidden_group_size_x
      - .offset:         254
        .size:           2
        .value_kind:     hidden_group_size_y
      - .offset:         256
        .size:           2
        .value_kind:     hidden_group_size_z
      - .offset:         258
        .size:           2
        .value_kind:     hidden_remainder_x
      - .offset:         260
        .size:           2
        .value_kind:     hidden_remainder_y
      - .offset:         262
        .size:           2
        .value_kind:     hidden_remainder_z
      - .offset:         280
        .size:           8
        .value_kind:     hidden_global_offset_x
      - .offset:         288
        .size:           8
        .value_kind:     hidden_global_offset_y
      - .offset:         296
        .size:           8
        .value_kind:     hidden_global_offset_z
      - .offset:         304
        .size:           2
        .value_kind:     hidden_grid_dims
      - .offset:         328
        .size:           8
        .value_kind:     hidden_multigrid_sync_arg
      - .offset:         360
        .size:           4
        .value_kind:     hidden_dynamic_lds_size
    .group_segment_fixed_size: 0
    .kernarg_segment_align: 8
    .kernarg_segment_size: 496
    .language:       OpenCL C
    .language_version:
      - 2
      - 0
    .max_flat_workgroup_size: 512
    .name:           _Z6mk_fwd4Args
    .private_segment_fixed_size: 0
    .sgpr_count:     106
    .sgpr_spill_count: 445
    .symbol:         _Z6mk_fwd4Args.kd
    .uniform_work_group_size: 1
    .uses_dynamic_stack: false
    .vgpr_count:     256
    .vgpr_spill_count: 0
    .wavefront_size: 64
